# all seven GEMM instances (incl. K=2816 FFN-down as a 4-k-tile rolled loop) on direct global-to-LDS staging
# speedup vs baseline: 1.0556x; 1.0115x over previous
;     ...
;     const u16* Ag = A + (size_t)(m0 + lrow) * K + lkc * 8;
;     const u16* Bg = Bt + (size_t)(n0 + lrow) * K + lkc * 8;
;     const size_t K32 = (size_t)32 * K;
;     uint4 xa0, xa1, xa2, xa3, xb0, xb1, xb2, xb3;
;     uint4 ya0, ya1, ya2, ya3, yb0, yb1, yb2, yb3;
;     ...
;     G_LOAD(x, 0);
;     G_STORE(x, 0);
;     __syncthreads();
;     if (KT > 1) G_LOAD(x, 1);
;     for (int kt = 0; kt < KT; kt += 2) {
;       if (kt + 2 < KT && dummy != 2) G_LOAD(y, kt + 2);
;       G_COMPUTE(0);
;       if (kt + 1 < KT && dummy != 2) G_STORE(x, 1);
;       __syncthreads();
;       if (kt + 1 >= KT) break;
;       if (kt + 3 < KT && dummy != 2) G_LOAD(x, kt + 3);
;       G_COMPUTE(1);
;       if (kt + 2 < KT && dummy != 2) G_STORE(y, 0);
;       __syncthreads();
;     }
.LBB0_151:
	v_readlane_b32 s2, v252, 34
	s_or_b32 s12, s12, s2
	v_readlane_b32 s2, v252, 28
	v_readlane_b32 s3, v252, 29
	s_and_b64 s[2:3], s[2:3], exec
	s_cselect_b32 s2, s12, s7
	s_lshl_b32 s14, s2, 7
	s_waitcnt vmcnt(0)
	s_lshl_b32 s2, s6, 7
	s_movk_i32 s88, 0x1600
	v_add_u32_e32 v82, s14, v148
	v_add_u32_e32 v83, s2, v148
	v_mad_i64_i32 v[64:65], s[90:91], v82, s88, v[130:131]
	v_mad_i64_i32 v[72:73], s[90:91], v83, s88, v[132:133]
	v_and_b32_e32 v82, 7, v206
	v_bfe_u32 v83, v206, 4, 3
	v_xor_b32_e32 v83, v83, v82
	v_sub_u32_e32 v83, v83, v82
	v_lshlrev_b32_e32 v80, 4, v83
	v_ashrrev_i32_e32 v81, 31, v80
	v_lshl_add_u64 v[64:65], v[64:65], 0, v[80:81]
	v_lshl_add_u64 v[72:73], v[72:73], 0, v[80:81]
	s_mov_b64 s[92:93], 0x2c000
	v_lshl_add_u64 v[66:67], v[64:65], 0, s[92:93]
	v_lshl_add_u64 v[74:75], v[72:73], 0, s[92:93]
	s_mov_b64 s[92:93], 0x58000
	v_lshl_add_u64 v[68:69], v[64:65], 0, s[92:93]
	v_lshl_add_u64 v[76:77], v[72:73], 0, s[92:93]
	s_mov_b64 s[92:93], 0x84000
	v_lshl_add_u64 v[70:71], v[64:65], 0, s[92:93]
	v_lshl_add_u64 v[78:79], v[72:73], 0, s[92:93]
	v_lshrrev_b32_e32 v82, 6, v206
	v_lshlrev_b32_e32 v82, 10, v82
	s_nop 0
	v_readfirstlane_b32 s77, v82
	v_bfe_u32 v83, v206, 1, 3
	v_bfe_u32 v82, v206, 5, 1
	v_and_b32_e32 v80, 1, v83
	v_xor_b32_e32 v82, v82, v80
	v_lshrrev_b32_e32 v83, 1, v83
	v_and_b32_e32 v80, 31, v206
	v_lshrrev_b32_e32 v81, 7, v206
	v_lshl_add_u32 v81, v81, 6, v80
	v_lshlrev_b32_e32 v81, 7, v81
	v_lshl_add_u32 v81, v82, 4, v81
	v_add_u32_e32 v81, 2048, v81
	v_bfe_u32 v92, v206, 6, 1
	v_lshl_add_u32 v92, v92, 6, v80
	v_lshlrev_b32_e32 v92, 7, v92
	v_lshl_add_u32 v92, v82, 4, v92
	v_add_u32_e32 v92, 18432, v92
	v_xor_b32_e32 v80, 0, v83
	v_lshl_add_u32 v84, v80, 5, v81
	v_lshl_add_u32 v88, v80, 5, v92
	v_xor_b32_e32 v80, 1, v83
	v_lshl_add_u32 v85, v80, 5, v81
	v_lshl_add_u32 v89, v80, 5, v92
	v_xor_b32_e32 v80, 2, v83
	v_lshl_add_u32 v86, v80, 5, v81
	v_lshl_add_u32 v90, v80, 5, v92
	v_xor_b32_e32 v80, 3, v83
	v_lshl_add_u32 v87, v80, 5, v81
	v_lshl_add_u32 v91, v80, 5, v92
	v_mov_b32_e32 v0, 0
	v_mov_b32_e32 v1, v0
	v_mov_b32_e32 v2, v0
	v_mov_b32_e32 v3, v0
	v_mov_b32_e32 v4, v0
	v_mov_b32_e32 v5, v0
	v_mov_b32_e32 v6, v0
	v_mov_b32_e32 v7, v0
	v_mov_b32_e32 v8, v0
	v_mov_b32_e32 v9, v0
	v_mov_b32_e32 v10, v0
	v_mov_b32_e32 v11, v0
	v_mov_b32_e32 v12, v0
	v_mov_b32_e32 v13, v0
	v_mov_b32_e32 v14, v0
	v_mov_b32_e32 v15, v0
	v_mov_b32_e32 v16, v0
	v_mov_b32_e32 v17, v0
	v_mov_b32_e32 v18, v0
	v_mov_b32_e32 v19, v0
	v_mov_b32_e32 v20, v0
	v_mov_b32_e32 v21, v0
	v_mov_b32_e32 v22, v0
	v_mov_b32_e32 v23, v0
	v_mov_b32_e32 v24, v0
	v_mov_b32_e32 v25, v0
	v_mov_b32_e32 v26, v0
	v_mov_b32_e32 v27, v0
	v_mov_b32_e32 v28, v0
	v_mov_b32_e32 v29, v0
	v_mov_b32_e32 v30, v0
	v_mov_b32_e32 v31, v0
	v_mov_b32_e32 v32, v0
	v_mov_b32_e32 v33, v0
	v_mov_b32_e32 v34, v0
	v_mov_b32_e32 v35, v0
	v_mov_b32_e32 v36, v0
	v_mov_b32_e32 v37, v0
	v_mov_b32_e32 v38, v0
	v_mov_b32_e32 v39, v0
	v_mov_b32_e32 v40, v0
	v_mov_b32_e32 v41, v0
	v_mov_b32_e32 v42, v0
	v_mov_b32_e32 v43, v0
	v_mov_b32_e32 v44, v0
	v_mov_b32_e32 v45, v0
	v_mov_b32_e32 v46, v0
	v_mov_b32_e32 v47, v0
	v_mov_b32_e32 v48, v0
	v_mov_b32_e32 v49, v0
	v_mov_b32_e32 v50, v0
	v_mov_b32_e32 v51, v0
	v_mov_b32_e32 v52, v0
	v_mov_b32_e32 v53, v0
	v_mov_b32_e32 v54, v0
	v_mov_b32_e32 v55, v0
	v_mov_b32_e32 v56, v0
	v_mov_b32_e32 v57, v0
	v_mov_b32_e32 v58, v0
	v_mov_b32_e32 v59, v0
	v_mov_b32_e32 v60, v0
	v_mov_b32_e32 v61, v0
	v_mov_b32_e32 v62, v0
	v_mov_b32_e32 v63, v0
	s_add_u32 m0, s77, 0x800
	s_nop 0
	global_load_lds_dwordx4 v[64:65], off
	s_add_u32 m0, s77, 0x1800
	s_nop 0
	global_load_lds_dwordx4 v[66:67], off
	s_add_u32 m0, s77, 0x2800
	s_nop 0
	global_load_lds_dwordx4 v[68:69], off
	s_add_u32 m0, s77, 0x3800
	s_nop 0
	global_load_lds_dwordx4 v[70:71], off
	s_add_u32 m0, s77, 0x4800
	s_nop 0
	global_load_lds_dwordx4 v[72:73], off
	s_add_u32 m0, s77, 0x5800
	s_nop 0
	global_load_lds_dwordx4 v[74:75], off
	s_add_u32 m0, s77, 0x6800
	s_nop 0
	global_load_lds_dwordx4 v[76:77], off
	s_add_u32 m0, s77, 0x7800
	s_nop 0
	global_load_lds_dwordx4 v[78:79], off
	s_waitcnt vmcnt(0)
	s_barrier
	s_mov_b32 s89, 0
.Lmy_r2a_loop:
	s_setprio 1
	ds_read_b128 v[100:103], v84
	ds_read_b128 v[104:107], v88
	ds_read_b128 v[108:111], v88 offset:4096
	ds_read_b128 v[112:115], v84 offset:4096
	ds_read_b128 v[116:119], v85
	ds_read_b128 v[120:123], v89
	ds_read_b128 v[124:127], v89 offset:4096
	ds_read_b128 v[92:95], v85 offset:4096
	s_add_u32 m0, s77, 0x8780
	s_nop 0
	global_load_lds_dwordx4 v[64:65], off offset:128
	s_add_u32 m0, s77, 0x9780
	s_nop 0
	global_load_lds_dwordx4 v[66:67], off offset:128
	s_add_u32 m0, s77, 0xa780
	s_nop 0
	global_load_lds_dwordx4 v[68:69], off offset:128
	s_add_u32 m0, s77, 0xb780
	s_nop 0
	global_load_lds_dwordx4 v[70:71], off offset:128
	s_add_u32 m0, s77, 0xc780
	s_nop 0
	global_load_lds_dwordx4 v[72:73], off offset:128
	s_add_u32 m0, s77, 0xd780
	s_nop 0
	global_load_lds_dwordx4 v[74:75], off offset:128
	s_add_u32 m0, s77, 0xe780
	s_nop 0
	global_load_lds_dwordx4 v[76:77], off offset:128
	s_add_u32 m0, s77, 0xf780
	s_nop 0
	global_load_lds_dwordx4 v[78:79], off offset:128
	s_waitcnt lgkmcnt(6)
	v_mfma_f32_32x32x16_bf16 v[48:63], v[100:103], v[104:107], v[48:63]
	s_waitcnt lgkmcnt(5)
	v_mfma_f32_32x32x16_bf16 v[32:47], v[100:103], v[108:111], v[32:47]
	s_waitcnt lgkmcnt(4)
	v_mfma_f32_32x32x16_bf16 v[16:31], v[112:115], v[104:107], v[16:31]
	v_mfma_f32_32x32x16_bf16 v[0:15], v[112:115], v[108:111], v[0:15]
	ds_read_b128 v[100:103], v86
	ds_read_b128 v[104:107], v90
	ds_read_b128 v[108:111], v90 offset:4096
	ds_read_b128 v[112:115], v86 offset:4096
	s_waitcnt lgkmcnt(6)
	v_mfma_f32_32x32x16_bf16 v[48:63], v[116:119], v[120:123], v[48:63]
	s_waitcnt lgkmcnt(5)
	v_mfma_f32_32x32x16_bf16 v[32:47], v[116:119], v[124:127], v[32:47]
	s_waitcnt lgkmcnt(4)
	v_mfma_f32_32x32x16_bf16 v[16:31], v[92:95], v[120:123], v[16:31]
	v_mfma_f32_32x32x16_bf16 v[0:15], v[92:95], v[124:127], v[0:15]
	ds_read_b128 v[116:119], v87
	ds_read_b128 v[120:123], v91
	ds_read_b128 v[124:127], v91 offset:4096
	ds_read_b128 v[92:95], v87 offset:4096
	s_waitcnt lgkmcnt(6)
	v_mfma_f32_32x32x16_bf16 v[48:63], v[100:103], v[104:107], v[48:63]
	s_waitcnt lgkmcnt(5)
	v_mfma_f32_32x32x16_bf16 v[32:47], v[100:103], v[108:111], v[32:47]
	s_waitcnt lgkmcnt(4)
	v_mfma_f32_32x32x16_bf16 v[16:31], v[112:115], v[104:107], v[16:31]
	v_mfma_f32_32x32x16_bf16 v[0:15], v[112:115], v[108:111], v[0:15]
	s_waitcnt lgkmcnt(2)
	v_mfma_f32_32x32x16_bf16 v[48:63], v[116:119], v[120:123], v[48:63]
	s_waitcnt lgkmcnt(1)
	v_mfma_f32_32x32x16_bf16 v[32:47], v[116:119], v[124:127], v[32:47]
	s_waitcnt lgkmcnt(0)
	v_mfma_f32_32x32x16_bf16 v[16:31], v[92:95], v[120:123], v[16:31]
	v_mfma_f32_32x32x16_bf16 v[0:15], v[92:95], v[124:127], v[0:15]
	s_setprio 0
	s_waitcnt vmcnt(0)
	s_barrier
;     ...
;     G_LOAD(x, 0);
;     G_STORE(x, 0);
;     __syncthreads();
;     if (KT > 1) G_LOAD(x, 1);
;     for (int kt = 0; kt < KT; kt += 2) {
;       if (kt + 2 < KT && dummy != 2) G_LOAD(y, kt + 2);
;       G_COMPUTE(0);
;       if (kt + 1 < KT && dummy != 2) G_STORE(x, 1);
;       __syncthreads();
;       if (kt + 1 >= KT) break;
;       if (kt + 3 < KT && dummy != 2) G_LOAD(x, kt + 3);
;       G_COMPUTE(1);
;       if (kt + 2 < KT && dummy != 2) G_STORE(y, 0);
;       __syncthreads();
;     }
	s_setprio 1
	ds_read_b128 v[100:103], v84 offset:32768
	ds_read_b128 v[104:107], v88 offset:32768
	ds_read_b128 v[108:111], v88 offset:36864
	ds_read_b128 v[112:115], v84 offset:36864
	ds_read_b128 v[116:119], v85 offset:32768
	ds_read_b128 v[120:123], v89 offset:32768
	ds_read_b128 v[124:127], v89 offset:36864
	ds_read_b128 v[92:95], v85 offset:36864
	s_add_u32 m0, s77, 0x700
	s_nop 0
	global_load_lds_dwordx4 v[64:65], off offset:256
	s_add_u32 m0, s77, 0x1700
	s_nop 0
	global_load_lds_dwordx4 v[66:67], off offset:256
	s_add_u32 m0, s77, 0x2700
	s_nop 0
	global_load_lds_dwordx4 v[68:69], off offset:256
	s_add_u32 m0, s77, 0x3700
	s_nop 0
	global_load_lds_dwordx4 v[70:71], off offset:256
	s_add_u32 m0, s77, 0x4700
	s_nop 0
	global_load_lds_dwordx4 v[72:73], off offset:256
	s_add_u32 m0, s77, 0x5700
	s_nop 0
	global_load_lds_dwordx4 v[74:75], off offset:256
	s_add_u32 m0, s77, 0x6700
	s_nop 0
	global_load_lds_dwordx4 v[76:77], off offset:256
	s_add_u32 m0, s77, 0x7700
	s_nop 0
	global_load_lds_dwordx4 v[78:79], off offset:256
	s_waitcnt lgkmcnt(6)
	v_mfma_f32_32x32x16_bf16 v[48:63], v[100:103], v[104:107], v[48:63]
	s_waitcnt lgkmcnt(5)
	v_mfma_f32_32x32x16_bf16 v[32:47], v[100:103], v[108:111], v[32:47]
	s_waitcnt lgkmcnt(4)
	v_mfma_f32_32x32x16_bf16 v[16:31], v[112:115], v[104:107], v[16:31]
	v_mfma_f32_32x32x16_bf16 v[0:15], v[112:115], v[108:111], v[0:15]
	ds_read_b128 v[100:103], v86 offset:32768
	ds_read_b128 v[104:107], v90 offset:32768
	ds_read_b128 v[108:111], v90 offset:36864
	ds_read_b128 v[112:115], v86 offset:36864
	s_waitcnt lgkmcnt(6)
	v_mfma_f32_32x32x16_bf16 v[48:63], v[116:119], v[120:123], v[48:63]
	s_waitcnt lgkmcnt(5)
	v_mfma_f32_32x32x16_bf16 v[32:47], v[116:119], v[124:127], v[32:47]
	s_waitcnt lgkmcnt(4)
	v_mfma_f32_32x32x16_bf16 v[16:31], v[92:95], v[120:123], v[16:31]
	v_mfma_f32_32x32x16_bf16 v[0:15], v[92:95], v[124:127], v[0:15]
	ds_read_b128 v[116:119], v87 offset:32768
	ds_read_b128 v[120:123], v91 offset:32768
	ds_read_b128 v[124:127], v91 offset:36864
	ds_read_b128 v[92:95], v87 offset:36864
	s_waitcnt lgkmcnt(6)
	v_mfma_f32_32x32x16_bf16 v[48:63], v[100:103], v[104:107], v[48:63]
	s_waitcnt lgkmcnt(5)
	v_mfma_f32_32x32x16_bf16 v[32:47], v[100:103], v[108:111], v[32:47]
	s_waitcnt lgkmcnt(4)
	v_mfma_f32_32x32x16_bf16 v[16:31], v[112:115], v[104:107], v[16:31]
	v_mfma_f32_32x32x16_bf16 v[0:15], v[112:115], v[108:111], v[0:15]
	s_waitcnt lgkmcnt(2)
	v_mfma_f32_32x32x16_bf16 v[48:63], v[116:119], v[120:123], v[48:63]
	s_waitcnt lgkmcnt(1)
	v_mfma_f32_32x32x16_bf16 v[32:47], v[116:119], v[124:127], v[32:47]
	s_waitcnt lgkmcnt(0)
	v_mfma_f32_32x32x16_bf16 v[16:31], v[92:95], v[120:123], v[16:31]
	v_mfma_f32_32x32x16_bf16 v[0:15], v[92:95], v[124:127], v[0:15]
	s_setprio 0
	s_waitcnt vmcnt(0)
	s_barrier
	s_setprio 1
	ds_read_b128 v[100:103], v84
	ds_read_b128 v[104:107], v88
	ds_read_b128 v[108:111], v88 offset:4096
	ds_read_b128 v[112:115], v84 offset:4096
	ds_read_b128 v[116:119], v85
	ds_read_b128 v[120:123], v89
	ds_read_b128 v[124:127], v89 offset:4096
	ds_read_b128 v[92:95], v85 offset:4096
	s_add_u32 m0, s77, 0x8680
	s_nop 0
	global_load_lds_dwordx4 v[64:65], off offset:384
	s_add_u32 m0, s77, 0x9680
	s_nop 0
	global_load_lds_dwordx4 v[66:67], off offset:384
	s_add_u32 m0, s77, 0xa680
	s_nop 0
	global_load_lds_dwordx4 v[68:69], off offset:384
	s_add_u32 m0, s77, 0xb680
	s_nop 0
	global_load_lds_dwordx4 v[70:71], off offset:384
	s_add_u32 m0, s77, 0xc680
	s_nop 0
	global_load_lds_dwordx4 v[72:73], off offset:384
	s_add_u32 m0, s77, 0xd680
	s_nop 0
	global_load_lds_dwordx4 v[74:75], off offset:384
	s_add_u32 m0, s77, 0xe680
	s_nop 0
	global_load_lds_dwordx4 v[76:77], off offset:384
	s_add_u32 m0, s77, 0xf680
	s_nop 0
	global_load_lds_dwordx4 v[78:79], off offset:384
	s_waitcnt lgkmcnt(6)
	v_mfma_f32_32x32x16_bf16 v[48:63], v[100:103], v[104:107], v[48:63]
	s_waitcnt lgkmcnt(5)
	v_mfma_f32_32x32x16_bf16 v[32:47], v[100:103], v[108:111], v[32:47]
	s_waitcnt lgkmcnt(4)
	v_mfma_f32_32x32x16_bf16 v[16:31], v[112:115], v[104:107], v[16:31]
	v_mfma_f32_32x32x16_bf16 v[0:15], v[112:115], v[108:111], v[0:15]
	ds_read_b128 v[100:103], v86
	ds_read_b128 v[104:107], v90
	ds_read_b128 v[108:111], v90 offset:4096
	ds_read_b128 v[112:115], v86 offset:4096
	s_waitcnt lgkmcnt(6)
	v_mfma_f32_32x32x16_bf16 v[48:63], v[116:119], v[120:123], v[48:63]
	s_waitcnt lgkmcnt(5)
	v_mfma_f32_32x32x16_bf16 v[32:47], v[116:119], v[124:127], v[32:47]
	s_waitcnt lgkmcnt(4)
	v_mfma_f32_32x32x16_bf16 v[16:31], v[92:95], v[120:123], v[16:31]
	v_mfma_f32_32x32x16_bf16 v[0:15], v[92:95], v[124:127], v[0:15]
	ds_read_b128 v[116:119], v87
	ds_read_b128 v[120:123], v91
	ds_read_b128 v[124:127], v91 offset:4096
	ds_read_b128 v[92:95], v87 offset:4096
	s_waitcnt lgkmcnt(6)
	v_mfma_f32_32x32x16_bf16 v[48:63], v[100:103], v[104:107], v[48:63]
	s_waitcnt lgkmcnt(5)
	v_mfma_f32_32x32x16_bf16 v[32:47], v[100:103], v[108:111], v[32:47]
	s_waitcnt lgkmcnt(4)
	v_mfma_f32_32x32x16_bf16 v[16:31], v[112:115], v[104:107], v[16:31]
	v_mfma_f32_32x32x16_bf16 v[0:15], v[112:115], v[108:111], v[0:15]
	s_waitcnt lgkmcnt(2)
	v_mfma_f32_32x32x16_bf16 v[48:63], v[116:119], v[120:123], v[48:63]
	s_waitcnt lgkmcnt(1)
	v_mfma_f32_32x32x16_bf16 v[32:47], v[116:119], v[124:127], v[32:47]
	s_waitcnt lgkmcnt(0)
	v_mfma_f32_32x32x16_bf16 v[16:31], v[92:95], v[120:123], v[16:31]
	v_mfma_f32_32x32x16_bf16 v[0:15], v[92:95], v[124:127], v[0:15]
	s_setprio 0
	s_waitcnt vmcnt(0)
	s_barrier
	s_setprio 1
	ds_read_b128 v[100:103], v84 offset:32768
	ds_read_b128 v[104:107], v88 offset:32768
	ds_read_b128 v[108:111], v88 offset:36864
	ds_read_b128 v[112:115], v84 offset:36864
	ds_read_b128 v[116:119], v85 offset:32768
	ds_read_b128 v[120:123], v89 offset:32768
	ds_read_b128 v[124:127], v89 offset:36864
	ds_read_b128 v[92:95], v85 offset:36864
	s_cmp_eq_u32 s89, 10
	s_cbranch_scc1 .Lmy_r2a_skip
	s_mov_b64 s[92:93], 0x200
	v_lshl_add_u64 v[64:65], v[64:65], 0, s[92:93]
	v_lshl_add_u64 v[66:67], v[66:67], 0, s[92:93]
	v_lshl_add_u64 v[68:69], v[68:69], 0, s[92:93]
	v_lshl_add_u64 v[70:71], v[70:71], 0, s[92:93]
	v_lshl_add_u64 v[72:73], v[72:73], 0, s[92:93]
	v_lshl_add_u64 v[74:75], v[74:75], 0, s[92:93]
	v_lshl_add_u64 v[76:77], v[76:77], 0, s[92:93]
	v_lshl_add_u64 v[78:79], v[78:79], 0, s[92:93]
	s_add_u32 m0, s77, 0x800
	s_nop 0
	global_load_lds_dwordx4 v[64:65], off
	s_add_u32 m0, s77, 0x1800
	s_nop 0
	global_load_lds_dwordx4 v[66:67], off
	s_add_u32 m0, s77, 0x2800
	s_nop 0
	global_load_lds_dwordx4 v[68:69], off
	s_add_u32 m0, s77, 0x3800
	s_nop 0
	global_load_lds_dwordx4 v[70:71], off
	s_add_u32 m0, s77, 0x4800
	s_nop 0
	global_load_lds_dwordx4 v[72:73], off
	s_add_u32 m0, s77, 0x5800
	s_nop 0
	global_load_lds_dwordx4 v[74:75], off
	s_add_u32 m0, s77, 0x6800
	s_nop 0
	global_load_lds_dwordx4 v[76:77], off
	s_add_u32 m0, s77, 0x7800
	s_nop 0
	global_load_lds_dwordx4 v[78:79], off
;     ...
;     G_LOAD(x, 0);
;     G_STORE(x, 0);
;     __syncthreads();
;     if (KT > 1) G_LOAD(x, 1);
;     for (int kt = 0; kt < KT; kt += 2) {
;       if (kt + 2 < KT && dummy != 2) G_LOAD(y, kt + 2);
;       G_COMPUTE(0);
;       if (kt + 1 < KT && dummy != 2) G_STORE(x, 1);
;       __syncthreads();
;       if (kt + 1 >= KT) break;
;       if (kt + 3 < KT && dummy != 2) G_LOAD(x, kt + 3);
;       G_COMPUTE(1);
;       if (kt + 2 < KT && dummy != 2) G_STORE(y, 0);
;       __syncthreads();
;     }
.Lmy_r2a_skip:
	s_waitcnt lgkmcnt(6)
	v_mfma_f32_32x32x16_bf16 v[48:63], v[100:103], v[104:107], v[48:63]
	s_waitcnt lgkmcnt(5)
	v_mfma_f32_32x32x16_bf16 v[32:47], v[100:103], v[108:111], v[32:47]
	s_waitcnt lgkmcnt(4)
	v_mfma_f32_32x32x16_bf16 v[16:31], v[112:115], v[104:107], v[16:31]
	v_mfma_f32_32x32x16_bf16 v[0:15], v[112:115], v[108:111], v[0:15]
	ds_read_b128 v[100:103], v86 offset:32768
	ds_read_b128 v[104:107], v90 offset:32768
	ds_read_b128 v[108:111], v90 offset:36864
	ds_read_b128 v[112:115], v86 offset:36864
	s_waitcnt lgkmcnt(6)
	v_mfma_f32_32x32x16_bf16 v[48:63], v[116:119], v[120:123], v[48:63]
	s_waitcnt lgkmcnt(5)
	v_mfma_f32_32x32x16_bf16 v[32:47], v[116:119], v[124:127], v[32:47]
	s_waitcnt lgkmcnt(4)
	v_mfma_f32_32x32x16_bf16 v[16:31], v[92:95], v[120:123], v[16:31]
	v_mfma_f32_32x32x16_bf16 v[0:15], v[92:95], v[124:127], v[0:15]
	ds_read_b128 v[116:119], v87 offset:32768
	ds_read_b128 v[120:123], v91 offset:32768
	ds_read_b128 v[124:127], v91 offset:36864
	ds_read_b128 v[92:95], v87 offset:36864
	s_waitcnt lgkmcnt(6)
	v_mfma_f32_32x32x16_bf16 v[48:63], v[100:103], v[104:107], v[48:63]
	s_waitcnt lgkmcnt(5)
	v_mfma_f32_32x32x16_bf16 v[32:47], v[100:103], v[108:111], v[32:47]
	s_waitcnt lgkmcnt(4)
	v_mfma_f32_32x32x16_bf16 v[16:31], v[112:115], v[104:107], v[16:31]
	v_mfma_f32_32x32x16_bf16 v[0:15], v[112:115], v[108:111], v[0:15]
	s_waitcnt lgkmcnt(2)
	v_mfma_f32_32x32x16_bf16 v[48:63], v[116:119], v[120:123], v[48:63]
	s_waitcnt lgkmcnt(1)
	v_mfma_f32_32x32x16_bf16 v[32:47], v[116:119], v[124:127], v[32:47]
	s_waitcnt lgkmcnt(0)
	v_mfma_f32_32x32x16_bf16 v[16:31], v[92:95], v[120:123], v[16:31]
	v_mfma_f32_32x32x16_bf16 v[0:15], v[92:95], v[124:127], v[0:15]
	s_setprio 0
	s_waitcnt vmcnt(0)
	s_barrier
	s_add_i32 s89, s89, 1
	s_cmp_lt_i32 s89, 11
	s_cbranch_scc1 .Lmy_r2a_loop

;     ...
;     const int mi_ = swz ? (mq * 8 + (bid & 7)) : mq;
;     const int mt = latent_only ? ((mi_ >> 4) * 18 + 2 + (mi_ & 15)) : mi_;
;     const int m0 = mt * 128, n0 = nt * 128;
;     f32x16 acc[2][2];
; #pragma unroll
;     for (int a = 0; a < 2; ++a)
; #pragma unroll
;       for (int b = 0; b < 2; ++b)
; #pragma unroll
;         for (int i = 0; i < 16; ++i) acc[a][b][i] = 0.f;
;     const u16* Ag = A + (size_t)(m0 + lrow) * K + lkc * 8;
;     const u16* Bg = Bt + (size_t)(n0 + lrow) * K + lkc * 8;
;     const size_t K32 = (size_t)32 * K;
;     uint4 xa0, xa1, xa2, xa3, xb0, xb1, xb2, xb3;
;     uint4 ya0, ya1, ya2, ya3, yb0, yb1, yb2, yb3;
;     ...
;     G_LOAD(x, 0);
;     G_STORE(x, 0);
;     __syncthreads();
;     if (KT > 1) G_LOAD(x, 1);
;     for (int kt = 0; kt < KT; kt += 2) {
;       if (kt + 2 < KT && dummy != 2) G_LOAD(y, kt + 2);
;       G_COMPUTE(0);
;       if (kt + 1 < KT && dummy != 2) G_STORE(x, 1);
;       __syncthreads();
;       if (kt + 1 >= KT) break;
;       if (kt + 3 < KT && dummy != 2) G_LOAD(x, kt + 3);
;       G_COMPUTE(1);
;       if (kt + 2 < KT && dummy != 2) G_STORE(y, 0);
;       __syncthreads();
;     }
.LBB0_171:
	v_readlane_b32 s0, v252, 34
	s_or_b32 s4, s4, s0
	v_readlane_b32 s0, v252, 28
	v_readlane_b32 s1, v252, 29
	s_and_b64 s[0:1], s[0:1], exec
	s_cselect_b32 s0, s4, s3
	s_lshr_b32 s1, s0, 4
	s_mul_i32 s1, s1, 18
	s_and_b32 s0, s0, 15
	s_add_i32 s0, s0, s1
	s_lshl_b32 s0, s0, 7
	s_add_i32 s13, s0, 0x100
	s_lshl_b32 s0, s2, 7
	s_waitcnt vmcnt(0)
	s_movk_i32 s88, 0x1600
	v_add_u32_e32 v82, s13, v146
	v_add_u32_e32 v83, s0, v146
	v_mad_i64_i32 v[64:65], s[90:91], v82, s88, v[130:131]
	v_mad_i64_i32 v[72:73], s[90:91], v83, s88, v[132:133]
	v_and_b32_e32 v82, 7, v206
	v_bfe_u32 v83, v206, 4, 3
	v_xor_b32_e32 v83, v83, v82
	v_sub_u32_e32 v83, v83, v82
	v_lshlrev_b32_e32 v80, 4, v83
	v_ashrrev_i32_e32 v81, 31, v80
	v_lshl_add_u64 v[64:65], v[64:65], 0, v[80:81]
	v_lshl_add_u64 v[72:73], v[72:73], 0, v[80:81]
	s_mov_b64 s[92:93], 0x2c000
	v_lshl_add_u64 v[66:67], v[64:65], 0, s[92:93]
	v_lshl_add_u64 v[74:75], v[72:73], 0, s[92:93]
	s_mov_b64 s[92:93], 0x58000
	v_lshl_add_u64 v[68:69], v[64:65], 0, s[92:93]
	v_lshl_add_u64 v[76:77], v[72:73], 0, s[92:93]
	s_mov_b64 s[92:93], 0x84000
	v_lshl_add_u64 v[70:71], v[64:65], 0, s[92:93]
	v_lshl_add_u64 v[78:79], v[72:73], 0, s[92:93]
	v_lshrrev_b32_e32 v82, 6, v206
	v_lshlrev_b32_e32 v82, 10, v82
	s_nop 0
	v_readfirstlane_b32 s77, v82
	v_bfe_u32 v83, v206, 1, 3
	v_bfe_u32 v82, v206, 5, 1
	v_and_b32_e32 v80, 1, v83
	v_xor_b32_e32 v82, v82, v80
	v_lshrrev_b32_e32 v83, 1, v83
	v_and_b32_e32 v80, 31, v206
	v_lshrrev_b32_e32 v81, 7, v206
	v_lshl_add_u32 v81, v81, 6, v80
	v_lshlrev_b32_e32 v81, 7, v81
	v_lshl_add_u32 v81, v82, 4, v81
	v_add_u32_e32 v81, 2048, v81
	v_bfe_u32 v92, v206, 6, 1
	v_lshl_add_u32 v92, v92, 6, v80
	v_lshlrev_b32_e32 v92, 7, v92
	v_lshl_add_u32 v92, v82, 4, v92
	v_add_u32_e32 v92, 18432, v92
	v_xor_b32_e32 v80, 0, v83
	v_lshl_add_u32 v84, v80, 5, v81
	v_lshl_add_u32 v88, v80, 5, v92
	v_xor_b32_e32 v80, 1, v83
	v_lshl_add_u32 v85, v80, 5, v81
	v_lshl_add_u32 v89, v80, 5, v92
	v_xor_b32_e32 v80, 2, v83
	v_lshl_add_u32 v86, v80, 5, v81
	v_lshl_add_u32 v90, v80, 5, v92
	v_xor_b32_e32 v80, 3, v83
	v_lshl_add_u32 v87, v80, 5, v81
	v_lshl_add_u32 v91, v80, 5, v92
	v_mov_b32_e32 v0, 0
	v_mov_b32_e32 v1, v0
	v_mov_b32_e32 v2, v0
	v_mov_b32_e32 v3, v0
	v_mov_b32_e32 v4, v0
	v_mov_b32_e32 v5, v0
	v_mov_b32_e32 v6, v0
	v_mov_b32_e32 v7, v0
	v_mov_b32_e32 v8, v0
	v_mov_b32_e32 v9, v0
	v_mov_b32_e32 v10, v0
	v_mov_b32_e32 v11, v0
	v_mov_b32_e32 v12, v0
	v_mov_b32_e32 v13, v0
	v_mov_b32_e32 v14, v0
	v_mov_b32_e32 v15, v0
	v_mov_b32_e32 v16, v0
	v_mov_b32_e32 v17, v0
	v_mov_b32_e32 v18, v0
	v_mov_b32_e32 v19, v0
	v_mov_b32_e32 v20, v0
	v_mov_b32_e32 v21, v0
	v_mov_b32_e32 v22, v0
	v_mov_b32_e32 v23, v0
	v_mov_b32_e32 v24, v0
	v_mov_b32_e32 v25, v0
	v_mov_b32_e32 v26, v0
	v_mov_b32_e32 v27, v0
	v_mov_b32_e32 v28, v0
	v_mov_b32_e32 v29, v0
	v_mov_b32_e32 v30, v0
	v_mov_b32_e32 v31, v0
	v_mov_b32_e32 v32, v0
	v_mov_b32_e32 v33, v0
	v_mov_b32_e32 v34, v0
	v_mov_b32_e32 v35, v0
	v_mov_b32_e32 v36, v0
	v_mov_b32_e32 v37, v0
	v_mov_b32_e32 v38, v0
	v_mov_b32_e32 v39, v0
	v_mov_b32_e32 v40, v0
	v_mov_b32_e32 v41, v0
	v_mov_b32_e32 v42, v0
	v_mov_b32_e32 v43, v0
	v_mov_b32_e32 v44, v0
	v_mov_b32_e32 v45, v0
	v_mov_b32_e32 v46, v0
	v_mov_b32_e32 v47, v0
	v_mov_b32_e32 v48, v0
	v_mov_b32_e32 v49, v0
	v_mov_b32_e32 v50, v0
	v_mov_b32_e32 v51, v0
	v_mov_b32_e32 v52, v0
	v_mov_b32_e32 v53, v0
	v_mov_b32_e32 v54, v0
	v_mov_b32_e32 v55, v0
	v_mov_b32_e32 v56, v0
	v_mov_b32_e32 v57, v0
	v_mov_b32_e32 v58, v0
	v_mov_b32_e32 v59, v0
	v_mov_b32_e32 v60, v0
	v_mov_b32_e32 v61, v0
	v_mov_b32_e32 v62, v0
	v_mov_b32_e32 v63, v0
	s_add_u32 m0, s77, 0x800
	s_nop 0
	global_load_lds_dwordx4 v[64:65], off
	s_add_u32 m0, s77, 0x1800
	s_nop 0
	global_load_lds_dwordx4 v[66:67], off
	s_add_u32 m0, s77, 0x2800
	s_nop 0
	global_load_lds_dwordx4 v[68:69], off
	s_add_u32 m0, s77, 0x3800
	s_nop 0
	global_load_lds_dwordx4 v[70:71], off
	s_add_u32 m0, s77, 0x4800
	s_nop 0
	global_load_lds_dwordx4 v[72:73], off
	s_add_u32 m0, s77, 0x5800
	s_nop 0
	global_load_lds_dwordx4 v[74:75], off
	s_add_u32 m0, s77, 0x6800
	s_nop 0
	global_load_lds_dwordx4 v[76:77], off
	s_add_u32 m0, s77, 0x7800
	s_nop 0
	global_load_lds_dwordx4 v[78:79], off
	s_waitcnt vmcnt(0)
	s_barrier
	s_mov_b32 s89, 0
